# final output stores in the P8 epilogue marked nt (never re-read)
# baseline (speedup 1.0000x reference)
; __device__ __forceinline__ void load8(const bf16_t* src, float* v) { const u32x4 w = *(const u32x4*)src; v[0] = bf_lo(w.x); v[1] = bf_hi(w.x); v[2] = bf_lo(w.y); v[3] = bf_hi(w.y); v[4] = bf_lo(w.z); v[5] = bf_hi(w.z); v[6] = bf_lo(w.w); v[7] = bf_hi(w.w); }
; __device__ __forceinline__ float sigmoidf_(float v) { return __builtin_amdgcn_rcpf(1.f + __builtin_amdgcn_exp2f(-v * LOG2E)); }
;     __device__ __forceinline__ void operator()(const pg8::f32x4 (&acc)[2][2][4][2], const pg8::Unit& u, int wr, int wc, int fr, int fq) const {
;     ...
;                     } else if constexpr (KIND == EK_FIN) {
;                         const int c = pn * 256 + cl; const size_t off = (size_t)row * 2048 + c; float e[8]; load8(a.g0 + off, e);
;                         const f32x4 x0 = *(const f32x4*)(a.outf + off), x1 = *(const f32x4*)(a.outf + off + 4);
;                         const f32x4 g0 = *(const f32x4*)(a.gv + c), g1 = *(const f32x4*)(a.gv + c + 4);
;                         f32x4 r0, r1;
; #pragma unroll
;                         for (int j = 0; j < 4; ++j) { r0[j] = x0[j] + sigmoidf_(v[j]) * (e[j] * rs * g0[j]); r1[j] = x1[j] + sigmoidf_(v[4 + j]) * (e[4 + j] * rs * g1[j]); }
;                         *(f32x4*)(a.outf + off) = r0; *(f32x4*)(a.outf + off + 4) = r1;
;                     }
.LBB0_1565:
	v_lshl_add_u32 v148, s26, 8, v152
	v_ashrrev_i32_e32 v149, 31, v148
	v_lshl_add_u64 v[144:145], v[148:149], 2, s[12:13]
	v_lshl_or_b32 v146, s48, 8, v154
	global_load_dword v159, v[144:145], off
	v_lshlrev_b64 v[180:181], 11, v[148:149]
	v_ashrrev_i32_e32 v147, 31, v146
	v_lshl_add_u64 v[150:151], v[180:181], 0, v[146:147]
	v_lshl_add_u64 v[144:145], v[150:151], 1, s[10:11]
	global_load_dwordx4 v[160:163], v[144:145], off
	v_lshl_add_u64 v[144:145], v[146:147], 2, s[6:7]
	global_load_dwordx4 v[164:167], v[144:145], off
	global_load_dwordx4 v[168:171], v[144:145], off offset:16
	v_lshl_add_u64 v[150:151], v[150:151], 2, s[4:5]
	global_load_dwordx4 v[172:175], v[150:151], off
	global_load_dwordx4 v[176:179], v[150:151], off offset:16
	v_mul_f32_e32 v120, 0xbfb8aa3b, v120
	v_mul_f32_e32 v125, 0xbfb8aa3b, v125
	v_mul_f32_e32 v121, 0xbfb8aa3b, v121
	v_mul_f32_e32 v124, 0xbfb8aa3b, v124
	v_mul_f32_e32 v126, 0xbfb8aa3b, v126
	v_mul_f32_e32 v122, 0xbfb8aa3b, v122
	v_mul_f32_e32 v127, 0xbfb8aa3b, v127
	v_mul_f32_e32 v123, 0xbfb8aa3b, v123
	v_exp_f32_e32 v149, v120
	v_exp_f32_e32 v125, v125
	v_exp_f32_e32 v182, v121
	v_exp_f32_e32 v124, v124
	v_exp_f32_e32 v183, v126
	v_exp_f32_e32 v184, v122
	v_exp_f32_e32 v185, v127
	v_exp_f32_e32 v186, v123
	v_or_b32_e32 v120, 0x80, v146
	v_ashrrev_i32_e32 v121, 31, v120
	v_lshl_add_u64 v[122:123], v[180:181], 0, v[120:121]
	v_lshl_add_u64 v[126:127], v[122:123], 1, s[10:11]
	v_add_f32_e32 v123, 1.0, v149
	v_add_f32_e32 v125, 1.0, v125
	v_add_f32_e32 v149, 1.0, v182
	v_add_f32_e32 v122, 1.0, v124
	v_add_f32_e32 v180, 1.0, v183
	v_add_f32_e32 v181, 1.0, v184
	v_add_f32_e32 v183, 1.0, v185
	v_add_f32_e32 v184, 1.0, v186
	v_rcp_f32_e32 v124, v123
	v_rcp_f32_e32 v123, v125
	v_rcp_f32_e32 v125, v149
	v_rcp_f32_e32 v182, v181
	v_rcp_f32_e32 v181, v183
	v_rcp_f32_e32 v183, v184
	v_rcp_f32_e32 v122, v122
	v_rcp_f32_e32 v180, v180
	v_mul_f32_e32 v116, 0xbfb8aa3b, v116
	v_mul_f32_e32 v112, 0xbfb8aa3b, v112
	v_mul_f32_e32 v117, 0xbfb8aa3b, v117
	v_mul_f32_e32 v113, 0xbfb8aa3b, v113
	v_mul_f32_e32 v118, 0xbfb8aa3b, v118
	v_mul_f32_e32 v119, 0xbfb8aa3b, v119
	v_mul_f32_e32 v114, 0xbfb8aa3b, v114
	v_mul_f32_e32 v115, 0xbfb8aa3b, v115
	v_exp_f32_e32 v116, v116
	v_exp_f32_e32 v117, v117
	v_exp_f32_e32 v118, v118
	v_exp_f32_e32 v119, v119
	v_exp_f32_e32 v114, v114
	v_exp_f32_e32 v115, v115
	v_add_f32_e32 v118, 1.0, v118
	v_add_f32_e32 v119, 1.0, v119
	v_rcp_f32_e32 v118, v118
	v_rcp_f32_e32 v119, v119
	v_mul_f32_e32 v108, 0xbfb8aa3b, v108
	v_mul_f32_e32 v104, 0xbfb8aa3b, v104
	v_mul_f32_e32 v109, 0xbfb8aa3b, v109
	v_mul_f32_e32 v105, 0xbfb8aa3b, v105
	v_mul_f32_e32 v110, 0xbfb8aa3b, v110
	v_mul_f32_e32 v111, 0xbfb8aa3b, v111
	v_mul_f32_e32 v106, 0xbfb8aa3b, v106
	v_mul_f32_e32 v107, 0xbfb8aa3b, v107
	v_exp_f32_e32 v108, v108
	v_exp_f32_e32 v109, v109
	v_exp_f32_e32 v110, v110
	v_exp_f32_e32 v111, v111
	v_exp_f32_e32 v106, v106
	v_exp_f32_e32 v107, v107
	v_add_f32_e32 v108, 1.0, v108
	v_add_f32_e32 v109, 1.0, v109
	s_waitcnt vmcnt(0)
	v_fmamk_f32 v149, v159, 0x3a000000, v158
	v_rsq_f32_e32 v184, v149
	v_exp_f32_e32 v149, v112
	v_exp_f32_e32 v159, v113
	v_or_b32_e32 v112, 16, v148
	v_lshlrev_b32_e32 v186, 16, v160
	v_and_b32_e32 v187, 0xffff0000, v160
	v_lshlrev_b32_e32 v188, 16, v162
	v_and_b32_e32 v189, 0xffff0000, v162
	v_lshlrev_b32_e32 v160, 16, v161
	v_and_b32_e32 v161, 0xffff0000, v161
	v_lshlrev_b32_e32 v162, 16, v163
	v_and_b32_e32 v163, 0xffff0000, v163
	v_pk_mul_f32 v[186:187], v[184:185], v[186:187] op_sel_hi:[0,1]
	v_pk_mul_f32 v[188:189], v[184:185], v[188:189] op_sel_hi:[0,1]
	v_pk_mul_f32 v[160:161], v[184:185], v[160:161] op_sel_hi:[0,1]
	v_pk_mul_f32 v[162:163], v[184:185], v[162:163] op_sel_hi:[0,1]
	v_pk_mul_f32 v[164:165], v[186:187], v[164:165]
	v_pk_mul_f32 v[168:169], v[188:189], v[168:169]
	v_pk_mul_f32 v[166:167], v[160:161], v[166:167]
	v_pk_mul_f32 v[162:163], v[162:163], v[170:171]
	v_pk_fma_f32 v[122:123], v[122:123], v[164:165], v[172:173]
	v_pk_fma_f32 v[160:161], v[124:125], v[168:169], v[176:177]
	v_pk_fma_f32 v[124:125], v[180:181], v[166:167], v[174:175]
	v_pk_fma_f32 v[162:163], v[182:183], v[162:163], v[178:179]
	global_store_dwordx4 v[150:151], v[122:125], off nt
	global_store_dwordx4 v[150:151], v[160:163], off offset:16 nt
	global_load_dwordx4 v[122:125], v[126:127], off
	s_nop 0
	global_load_dwordx4 v[160:163], v[144:145], off offset:512
	global_load_dwordx4 v[164:167], v[144:145], off offset:528
	global_load_dwordx4 v[168:171], v[150:151], off offset:512
	global_load_dwordx4 v[172:175], v[150:151], off offset:528
	v_ashrrev_i32_e32 v113, 31, v112
	v_lshl_add_u64 v[126:127], v[112:113], 2, s[12:13]
	v_lshlrev_b64 v[176:177], 11, v[112:113]
	v_add_f32_e32 v112, 1.0, v116
	v_add_f32_e32 v113, 1.0, v149
	v_add_f32_e32 v116, 1.0, v117
	v_add_f32_e32 v117, 1.0, v159
	v_add_f32_e32 v149, 1.0, v114
	v_add_f32_e32 v159, 1.0, v115
	v_rcp_f32_e32 v112, v112
	v_rcp_f32_e32 v114, v113
	v_rcp_f32_e32 v113, v116
	v_rcp_f32_e32 v115, v117
	v_rcp_f32_e32 v182, v149
	v_rcp_f32_e32 v183, v159
	v_lshl_add_u64 v[178:179], v[176:177], 0, v[146:147]
	v_lshl_add_u64 v[180:181], v[178:179], 1, s[10:11]
	v_add_f32_e32 v110, 1.0, v110
	v_add_f32_e32 v111, 1.0, v111
	v_rcp_f32_e32 v110, v110
	v_rcp_f32_e32 v111, v111
	v_mul_f32_e32 v100, 0xbfb8aa3b, v100
	v_mul_f32_e32 v96, 0xbfb8aa3b, v96
	v_mul_f32_e32 v101, 0xbfb8aa3b, v101
	v_mul_f32_e32 v97, 0xbfb8aa3b, v97
	v_mul_f32_e32 v102, 0xbfb8aa3b, v102
	v_mul_f32_e32 v103, 0xbfb8aa3b, v103
	v_mul_f32_e32 v98, 0xbfb8aa3b, v98
	v_mul_f32_e32 v99, 0xbfb8aa3b, v99
	v_exp_f32_e32 v100, v100
	v_exp_f32_e32 v101, v101
	v_exp_f32_e32 v159, v97
	v_exp_f32_e32 v102, v102
	v_exp_f32_e32 v103, v103
	v_exp_f32_e32 v98, v98
	v_exp_f32_e32 v99, v99
	v_add_f32_e32 v102, 1.0, v102
	v_add_f32_e32 v103, 1.0, v103
	v_rcp_f32_e32 v102, v102
	v_rcp_f32_e32 v103, v103
	v_mul_f32_e32 v89, 0xbfb8aa3b, v89
	v_mul_f32_e32 v91, 0xbfb8aa3b, v91
	v_exp_f32_e32 v91, v91
	v_mul_f32_e32 v92, 0xbfb8aa3b, v92
	v_mul_f32_e32 v88, 0xbfb8aa3b, v88
	v_mul_f32_e32 v93, 0xbfb8aa3b, v93
	v_mul_f32_e32 v94, 0xbfb8aa3b, v94
	v_mul_f32_e32 v95, 0xbfb8aa3b, v95
	v_mul_f32_e32 v90, 0xbfb8aa3b, v90
	v_exp_f32_e32 v92, v92
	v_exp_f32_e32 v93, v93
	v_exp_f32_e32 v94, v94
	v_exp_f32_e32 v95, v95
	v_exp_f32_e32 v90, v90
	v_add_f32_e32 v92, 1.0, v92
	v_add_f32_e32 v93, 1.0, v93
	v_add_f32_e32 v94, 1.0, v94
	v_add_f32_e32 v95, 1.0, v95
	v_rcp_f32_e32 v94, v94
	v_rcp_f32_e32 v95, v95
	v_mul_f32_e32 v84, 0xbfb8aa3b, v84
	v_mul_f32_e32 v80, 0xbfb8aa3b, v80
	v_mul_f32_e32 v85, 0xbfb8aa3b, v85
	v_mul_f32_e32 v81, 0xbfb8aa3b, v81
	v_mul_f32_e32 v86, 0xbfb8aa3b, v86
	v_mul_f32_e32 v87, 0xbfb8aa3b, v87
	v_mul_f32_e32 v82, 0xbfb8aa3b, v82
	v_mul_f32_e32 v83, 0xbfb8aa3b, v83
	v_exp_f32_e32 v84, v84
	v_exp_f32_e32 v85, v85
	v_exp_f32_e32 v86, v86
	v_exp_f32_e32 v87, v87
	v_exp_f32_e32 v82, v82
	v_exp_f32_e32 v83, v83
	v_add_f32_e32 v86, 1.0, v86
	s_waitcnt vmcnt(4)
; __device__ __forceinline__ void load8(const bf16_t* src, float* v) { const u32x4 w = *(const u32x4*)src; v[0] = bf_lo(w.x); v[1] = bf_hi(w.x); v[2] = bf_lo(w.y); v[3] = bf_hi(w.y); v[4] = bf_lo(w.z); v[5] = bf_hi(w.z); v[6] = bf_lo(w.w); v[7] = bf_hi(w.w); }
; __device__ __forceinline__ float sigmoidf_(float v) { return __builtin_amdgcn_rcpf(1.f + __builtin_amdgcn_exp2f(-v * LOG2E)); }
;     __device__ __forceinline__ void operator()(const pg8::f32x4 (&acc)[2][2][4][2], const pg8::Unit& u, int wr, int wc, int fr, int fq) const {
;     ...
;                 if constexpr (KIND == EK_FIN) rs = __builtin_amdgcn_rsqf(a.ssq0[row] * (1.f / 2048.f) + EPS);
;     ...
;                     } else if constexpr (KIND == EK_FIN) {
;                         const int c = pn * 256 + cl; const size_t off = (size_t)row * 2048 + c; float e[8]; load8(a.g0 + off, e);
;                         const f32x4 x0 = *(const f32x4*)(a.outf + off), x1 = *(const f32x4*)(a.outf + off + 4);
;                         const f32x4 g0 = *(const f32x4*)(a.gv + c), g1 = *(const f32x4*)(a.gv + c + 4);
;                         f32x4 r0, r1;
; #pragma unroll
;                         for (int j = 0; j < 4; ++j) { r0[j] = x0[j] + sigmoidf_(v[j]) * (e[j] * rs * g0[j]); r1[j] = x1[j] + sigmoidf_(v[4 + j]) * (e[4 + j] * rs * g1[j]); }
;                         *(f32x4*)(a.outf + off) = r0; *(f32x4*)(a.outf + off + 4) = r1;
;                     }
	v_lshlrev_b32_e32 v116, 16, v122
	v_and_b32_e32 v117, 0xffff0000, v122
	v_lshlrev_b32_e32 v186, 16, v124
	v_and_b32_e32 v187, 0xffff0000, v124
	v_lshlrev_b32_e32 v122, 16, v123
	v_and_b32_e32 v123, 0xffff0000, v123
	v_lshlrev_b32_e32 v124, 16, v125
	v_and_b32_e32 v125, 0xffff0000, v125
	v_pk_mul_f32 v[116:117], v[184:185], v[116:117] op_sel_hi:[0,1]
	v_pk_mul_f32 v[186:187], v[184:185], v[186:187] op_sel_hi:[0,1]
	v_pk_mul_f32 v[122:123], v[184:185], v[122:123] op_sel_hi:[0,1]
	v_pk_mul_f32 v[124:125], v[184:185], v[124:125] op_sel_hi:[0,1]
	s_waitcnt vmcnt(3)
	v_pk_mul_f32 v[116:117], v[116:117], v[160:161]
	s_waitcnt vmcnt(2)
	v_pk_mul_f32 v[160:161], v[186:187], v[164:165]
	v_pk_mul_f32 v[122:123], v[122:123], v[162:163]
	v_pk_mul_f32 v[124:125], v[124:125], v[166:167]
	s_waitcnt vmcnt(1)
	v_pk_fma_f32 v[112:113], v[112:113], v[116:117], v[168:169]
	s_waitcnt vmcnt(0)
	v_pk_fma_f32 v[116:117], v[114:115], v[160:161], v[172:173]
	v_pk_fma_f32 v[114:115], v[118:119], v[122:123], v[170:171]
	v_pk_fma_f32 v[118:119], v[182:183], v[124:125], v[174:175]
	global_store_dwordx4 v[150:151], v[112:115], off offset:512 nt
	global_store_dwordx4 v[150:151], v[116:119], off offset:528 nt
	global_load_dword v149, v[126:127], off
	s_nop 0
	global_load_dwordx4 v[114:117], v[180:181], off
	global_load_dwordx4 v[122:125], v[144:145], off
	global_load_dwordx4 v[160:163], v[144:145], off offset:16
	v_lshl_add_u64 v[112:113], v[178:179], 2, s[4:5]
	global_load_dwordx4 v[164:167], v[112:113], off
	global_load_dwordx4 v[168:171], v[112:113], off offset:16
	v_exp_f32_e32 v118, v104
	v_exp_f32_e32 v119, v105
	v_lshl_add_u64 v[104:105], v[176:177], 0, v[120:121]
	v_add_f32_e32 v150, 1.0, v106
	v_add_f32_e32 v126, 1.0, v118
	v_add_f32_e32 v127, 1.0, v119
	v_add_f32_e32 v151, 1.0, v107
	v_lshl_add_u64 v[118:119], v[104:105], 1, s[10:11]
	v_rcp_f32_e32 v104, v108
	v_rcp_f32_e32 v106, v126
	v_rcp_f32_e32 v105, v109
	v_rcp_f32_e32 v107, v127
	v_rcp_f32_e32 v126, v150
	v_rcp_f32_e32 v127, v151
	v_add_f32_e32 v87, 1.0, v87
	v_rcp_f32_e32 v86, v86
	v_rcp_f32_e32 v87, v87
	v_mul_f32_e32 v73, 0xbfb8aa3b, v73
	v_mul_f32_e32 v75, 0xbfb8aa3b, v75
	v_exp_f32_e32 v75, v75
	v_mul_f32_e32 v76, 0xbfb8aa3b, v76
	v_mul_f32_e32 v72, 0xbfb8aa3b, v72
	v_mul_f32_e32 v77, 0xbfb8aa3b, v77
	v_mul_f32_e32 v78, 0xbfb8aa3b, v78
	v_mul_f32_e32 v79, 0xbfb8aa3b, v79
	v_mul_f32_e32 v74, 0xbfb8aa3b, v74
	v_exp_f32_e32 v76, v76
	v_exp_f32_e32 v77, v77
	v_exp_f32_e32 v78, v78
	v_exp_f32_e32 v79, v79
	v_exp_f32_e32 v74, v74
	v_add_f32_e32 v76, 1.0, v76
	v_add_f32_e32 v77, 1.0, v77
	v_add_f32_e32 v78, 1.0, v78
	v_add_f32_e32 v79, 1.0, v79
	v_rcp_f32_e32 v78, v78
	v_rcp_f32_e32 v79, v79
	v_mul_f32_e32 v68, 0xbfb8aa3b, v68
	v_mul_f32_e32 v64, 0xbfb8aa3b, v64
	v_mul_f32_e32 v69, 0xbfb8aa3b, v69
	v_mul_f32_e32 v65, 0xbfb8aa3b, v65
	v_mul_f32_e32 v70, 0xbfb8aa3b, v70
	v_mul_f32_e32 v71, 0xbfb8aa3b, v71
	v_mul_f32_e32 v66, 0xbfb8aa3b, v66
	v_mul_f32_e32 v67, 0xbfb8aa3b, v67
	v_exp_f32_e32 v68, v68
	v_exp_f32_e32 v69, v69
	v_exp_f32_e32 v70, v70
	v_exp_f32_e32 v71, v71
	v_exp_f32_e32 v66, v66
	v_exp_f32_e32 v67, v67
	v_add_f32_e32 v70, 1.0, v70
	v_add_f32_e32 v71, 1.0, v71
	v_rcp_f32_e32 v70, v70
	v_rcp_f32_e32 v71, v71
	v_mul_f32_e32 v57, 0xbfb8aa3b, v57
	v_mul_f32_e32 v59, 0xbfb8aa3b, v59
	v_exp_f32_e32 v59, v59
	v_mul_f32_e32 v60, 0xbfb8aa3b, v60
	v_mul_f32_e32 v56, 0xbfb8aa3b, v56
	v_mul_f32_e32 v61, 0xbfb8aa3b, v61
	v_mul_f32_e32 v62, 0xbfb8aa3b, v62
	v_mul_f32_e32 v63, 0xbfb8aa3b, v63
	v_mul_f32_e32 v58, 0xbfb8aa3b, v58
	v_exp_f32_e32 v60, v60
	v_exp_f32_e32 v61, v61
	v_exp_f32_e32 v62, v62
	v_exp_f32_e32 v63, v63
	v_exp_f32_e32 v58, v58
	v_add_f32_e32 v60, 1.0, v60
	v_add_f32_e32 v61, 1.0, v61
	v_add_f32_e32 v62, 1.0, v62
	v_add_f32_e32 v63, 1.0, v63
	v_rcp_f32_e32 v62, v62
	s_waitcnt vmcnt(5)
	v_fmamk_f32 v149, v149, 0x3a000000, v158
	v_rsq_f32_e32 v172, v149
	s_waitcnt vmcnt(4)
	v_lshlrev_b32_e32 v108, 16, v114
	v_and_b32_e32 v109, 0xffff0000, v114
	v_lshlrev_b32_e32 v150, 16, v116
	v_and_b32_e32 v151, 0xffff0000, v116
	v_lshlrev_b32_e32 v114, 16, v115
	v_and_b32_e32 v115, 0xffff0000, v115
	v_lshlrev_b32_e32 v116, 16, v117
	v_and_b32_e32 v117, 0xffff0000, v117
	v_pk_mul_f32 v[108:109], v[172:173], v[108:109] op_sel_hi:[0,1]
	v_pk_mul_f32 v[150:151], v[172:173], v[150:151] op_sel_hi:[0,1]
	v_pk_mul_f32 v[114:115], v[172:173], v[114:115] op_sel_hi:[0,1]
	v_pk_mul_f32 v[116:117], v[172:173], v[116:117] op_sel_hi:[0,1]
	s_waitcnt vmcnt(3)
	v_pk_mul_f32 v[108:109], v[108:109], v[122:123]
	s_waitcnt vmcnt(2)
	v_pk_mul_f32 v[122:123], v[150:151], v[160:161]
	v_pk_mul_f32 v[114:115], v[114:115], v[124:125]
	v_pk_mul_f32 v[116:117], v[116:117], v[162:163]
	s_waitcnt vmcnt(1)
	v_pk_fma_f32 v[104:105], v[104:105], v[108:109], v[164:165]
	s_waitcnt vmcnt(0)
; __device__ __forceinline__ void load8(const bf16_t* src, float* v) { const u32x4 w = *(const u32x4*)src; v[0] = bf_lo(w.x); v[1] = bf_hi(w.x); v[2] = bf_lo(w.y); v[3] = bf_hi(w.y); v[4] = bf_lo(w.z); v[5] = bf_hi(w.z); v[6] = bf_lo(w.w); v[7] = bf_hi(w.w); }
; __device__ __forceinline__ float sigmoidf_(float v) { return __builtin_amdgcn_rcpf(1.f + __builtin_amdgcn_exp2f(-v * LOG2E)); }
;     __device__ __forceinline__ void operator()(const pg8::f32x4 (&acc)[2][2][4][2], const pg8::Unit& u, int wr, int wc, int fr, int fq) const {
;     ...
;                     } else if constexpr (KIND == EK_FIN) {
;                         const int c = pn * 256 + cl; const size_t off = (size_t)row * 2048 + c; float e[8]; load8(a.g0 + off, e);
;                         const f32x4 x0 = *(const f32x4*)(a.outf + off), x1 = *(const f32x4*)(a.outf + off + 4);
;                         const f32x4 g0 = *(const f32x4*)(a.gv + c), g1 = *(const f32x4*)(a.gv + c + 4);
;                         f32x4 r0, r1;
; #pragma unroll
;                         for (int j = 0; j < 4; ++j) { r0[j] = x0[j] + sigmoidf_(v[j]) * (e[j] * rs * g0[j]); r1[j] = x1[j] + sigmoidf_(v[4 + j]) * (e[4 + j] * rs * g1[j]); }
;                         *(f32x4*)(a.outf + off) = r0; *(f32x4*)(a.outf + off + 4) = r1;
;                     }
	v_pk_fma_f32 v[108:109], v[106:107], v[122:123], v[168:169]
	v_pk_fma_f32 v[106:107], v[110:111], v[114:115], v[166:167]
	v_pk_fma_f32 v[110:111], v[126:127], v[116:117], v[170:171]
	global_store_dwordx4 v[112:113], v[104:107], off nt
	global_store_dwordx4 v[112:113], v[108:111], off offset:16 nt
	global_load_dwordx4 v[104:107], v[118:119], off
	s_nop 0
	global_load_dwordx4 v[108:111], v[144:145], off offset:512
	global_load_dwordx4 v[114:117], v[144:145], off offset:528
	global_load_dwordx4 v[122:125], v[112:113], off offset:512
	global_load_dwordx4 v[160:163], v[112:113], off offset:528
	v_exp_f32_e32 v149, v96
	v_or_b32_e32 v96, 32, v148
	v_ashrrev_i32_e32 v97, 31, v96
	v_lshl_add_u64 v[118:119], v[96:97], 2, s[12:13]
	v_lshlrev_b64 v[126:127], 11, v[96:97]
	v_add_f32_e32 v96, 1.0, v100
	v_add_f32_e32 v97, 1.0, v149
	v_add_f32_e32 v100, 1.0, v101
	v_add_f32_e32 v101, 1.0, v159
	v_add_f32_e32 v149, 1.0, v98
	v_add_f32_e32 v159, 1.0, v99
	v_rcp_f32_e32 v96, v96
	v_rcp_f32_e32 v98, v97
	v_rcp_f32_e32 v97, v100
	v_rcp_f32_e32 v99, v101
	v_rcp_f32_e32 v166, v149
	v_rcp_f32_e32 v167, v159
	v_lshl_add_u64 v[150:151], v[126:127], 0, v[146:147]
	v_lshl_add_u64 v[164:165], v[150:151], 1, s[10:11]
	v_rcp_f32_e32 v63, v63
	v_mul_f32_e32 v52, 0xbfb8aa3b, v52
	v_mul_f32_e32 v48, 0xbfb8aa3b, v48
	v_mul_f32_e32 v53, 0xbfb8aa3b, v53
	v_mul_f32_e32 v49, 0xbfb8aa3b, v49
	v_mul_f32_e32 v54, 0xbfb8aa3b, v54
	v_mul_f32_e32 v55, 0xbfb8aa3b, v55
	v_mul_f32_e32 v50, 0xbfb8aa3b, v50
	v_mul_f32_e32 v51, 0xbfb8aa3b, v51
	v_exp_f32_e32 v52, v52
	v_exp_f32_e32 v53, v53
	v_exp_f32_e32 v54, v54
	v_exp_f32_e32 v55, v55
	v_exp_f32_e32 v50, v50
	v_exp_f32_e32 v51, v51
	v_add_f32_e32 v54, 1.0, v54
	v_add_f32_e32 v55, 1.0, v55
	v_rcp_f32_e32 v54, v54
	v_rcp_f32_e32 v55, v55
	v_mul_f32_e32 v41, 0xbfb8aa3b, v41
	v_mul_f32_e32 v43, 0xbfb8aa3b, v43
	v_exp_f32_e32 v43, v43
	v_mul_f32_e32 v44, 0xbfb8aa3b, v44
	v_mul_f32_e32 v40, 0xbfb8aa3b, v40
	v_mul_f32_e32 v45, 0xbfb8aa3b, v45
	v_mul_f32_e32 v46, 0xbfb8aa3b, v46
	v_mul_f32_e32 v47, 0xbfb8aa3b, v47
	v_mul_f32_e32 v42, 0xbfb8aa3b, v42
	v_exp_f32_e32 v44, v44
	v_exp_f32_e32 v45, v45
	v_exp_f32_e32 v46, v46
	v_exp_f32_e32 v47, v47
	v_exp_f32_e32 v42, v42
	v_add_f32_e32 v44, 1.0, v44
	v_add_f32_e32 v45, 1.0, v45
	v_add_f32_e32 v46, 1.0, v46
	v_add_f32_e32 v47, 1.0, v47
	v_rcp_f32_e32 v46, v46
	v_rcp_f32_e32 v47, v47
	v_mul_f32_e32 v36, 0xbfb8aa3b, v36
	v_mul_f32_e32 v32, 0xbfb8aa3b, v32
	v_mul_f32_e32 v37, 0xbfb8aa3b, v37
	v_mul_f32_e32 v33, 0xbfb8aa3b, v33
	v_mul_f32_e32 v38, 0xbfb8aa3b, v38
	v_mul_f32_e32 v39, 0xbfb8aa3b, v39
	v_mul_f32_e32 v34, 0xbfb8aa3b, v34
	v_mul_f32_e32 v35, 0xbfb8aa3b, v35
	v_exp_f32_e32 v36, v36
	v_exp_f32_e32 v37, v37
	v_exp_f32_e32 v38, v38
	v_exp_f32_e32 v39, v39
	v_exp_f32_e32 v34, v34
	v_exp_f32_e32 v35, v35
	v_add_f32_e32 v38, 1.0, v38
	v_add_f32_e32 v39, 1.0, v39
	v_rcp_f32_e32 v38, v38
	s_waitcnt vmcnt(4)
	v_lshlrev_b32_e32 v100, 16, v104
	v_and_b32_e32 v101, 0xffff0000, v104
	v_lshlrev_b32_e32 v168, 16, v106
	v_and_b32_e32 v169, 0xffff0000, v106
	v_lshlrev_b32_e32 v104, 16, v105
	v_and_b32_e32 v105, 0xffff0000, v105
	v_lshlrev_b32_e32 v106, 16, v107
	v_and_b32_e32 v107, 0xffff0000, v107
	v_pk_mul_f32 v[100:101], v[172:173], v[100:101] op_sel_hi:[0,1]
	v_pk_mul_f32 v[168:169], v[172:173], v[168:169] op_sel_hi:[0,1]
	v_pk_mul_f32 v[104:105], v[172:173], v[104:105] op_sel_hi:[0,1]
	v_pk_mul_f32 v[106:107], v[172:173], v[106:107] op_sel_hi:[0,1]
	s_waitcnt vmcnt(3)
	v_pk_mul_f32 v[100:101], v[100:101], v[108:109]
	s_waitcnt vmcnt(2)
	v_pk_mul_f32 v[108:109], v[168:169], v[114:115]
	v_pk_mul_f32 v[104:105], v[104:105], v[110:111]
	v_pk_mul_f32 v[106:107], v[106:107], v[116:117]
	s_waitcnt vmcnt(1)
	v_pk_fma_f32 v[96:97], v[96:97], v[100:101], v[122:123]
	s_waitcnt vmcnt(0)
	v_pk_fma_f32 v[100:101], v[98:99], v[108:109], v[160:161]
	v_pk_fma_f32 v[98:99], v[102:103], v[104:105], v[124:125]
	v_pk_fma_f32 v[102:103], v[166:167], v[106:107], v[162:163]
	global_store_dwordx4 v[112:113], v[96:99], off offset:512 nt
	global_store_dwordx4 v[112:113], v[100:103], off offset:528 nt
	global_load_dword v124, v[118:119], off
	s_nop 0
	global_load_dwordx4 v[98:101], v[164:165], off
	global_load_dwordx4 v[102:105], v[144:145], off
	global_load_dwordx4 v[106:109], v[144:145], off offset:16
	v_lshl_add_u64 v[96:97], v[150:151], 2, s[4:5]
	global_load_dwordx4 v[110:113], v[96:97], off
	global_load_dwordx4 v[114:117], v[96:97], off offset:16
	v_exp_f32_e32 v119, v89
	v_exp_f32_e32 v118, v88
	v_lshl_add_u64 v[88:89], v[126:127], 0, v[120:121]
	v_add_f32_e32 v126, 1.0, v91
	v_add_f32_e32 v123, 1.0, v119
	v_rcp_f32_e32 v91, v123
	v_rcp_f32_e32 v123, v126
	v_add_f32_e32 v122, 1.0, v118
	v_add_f32_e32 v125, 1.0, v90
	v_lshl_add_u64 v[118:119], v[88:89], 1, s[10:11]
	v_rcp_f32_e32 v88, v92
	v_rcp_f32_e32 v90, v122
	v_rcp_f32_e32 v89, v93
	v_rcp_f32_e32 v122, v125
	v_rcp_f32_e32 v39, v39
	v_mul_f32_e32 v25, 0xbfb8aa3b, v25
	v_mul_f32_e32 v27, 0xbfb8aa3b, v27
	v_exp_f32_e32 v27, v27
	v_mul_f32_e32 v28, 0xbfb8aa3b, v28
	v_mul_f32_e32 v24, 0xbfb8aa3b, v24
	v_mul_f32_e32 v29, 0xbfb8aa3b, v29
	v_mul_f32_e32 v30, 0xbfb8aa3b, v30
	v_mul_f32_e32 v31, 0xbfb8aa3b, v31
	v_mul_f32_e32 v26, 0xbfb8aa3b, v26
	v_exp_f32_e32 v28, v28
	v_exp_f32_e32 v29, v29
	v_exp_f32_e32 v30, v30
	v_exp_f32_e32 v31, v31
	v_exp_f32_e32 v26, v26
	v_add_f32_e32 v28, 1.0, v28
	v_add_f32_e32 v29, 1.0, v29
	v_add_f32_e32 v30, 1.0, v30
	v_add_f32_e32 v31, 1.0, v31
	v_rcp_f32_e32 v30, v30
	v_rcp_f32_e32 v31, v31
	v_mul_f32_e32 v20, 0xbfb8aa3b, v20
	v_mul_f32_e32 v16, 0xbfb8aa3b, v16
	v_mul_f32_e32 v21, 0xbfb8aa3b, v21
	v_mul_f32_e32 v17, 0xbfb8aa3b, v17
	v_mul_f32_e32 v22, 0xbfb8aa3b, v22
	v_mul_f32_e32 v23, 0xbfb8aa3b, v23
	v_mul_f32_e32 v18, 0xbfb8aa3b, v18
	v_mul_f32_e32 v19, 0xbfb8aa3b, v19
	v_exp_f32_e32 v20, v20
	v_exp_f32_e32 v21, v21
	v_exp_f32_e32 v22, v22
	v_exp_f32_e32 v23, v23
	v_exp_f32_e32 v18, v18
	v_exp_f32_e32 v19, v19
	v_add_f32_e32 v22, 1.0, v22
	v_add_f32_e32 v23, 1.0, v23
	v_rcp_f32_e32 v22, v22
	v_rcp_f32_e32 v23, v23
	v_mul_f32_e32 v9, 0xbfb8aa3b, v9
	v_mul_f32_e32 v11, 0xbfb8aa3b, v11
	v_exp_f32_e32 v11, v11
	v_mul_f32_e32 v12, 0xbfb8aa3b, v12
	v_mul_f32_e32 v8, 0xbfb8aa3b, v8
	v_mul_f32_e32 v13, 0xbfb8aa3b, v13
	v_mul_f32_e32 v14, 0xbfb8aa3b, v14
	v_mul_f32_e32 v15, 0xbfb8aa3b, v15
	v_mul_f32_e32 v10, 0xbfb8aa3b, v10
	v_exp_f32_e32 v12, v12
	v_exp_f32_e32 v13, v13
	v_exp_f32_e32 v14, v14
	v_exp_f32_e32 v15, v15
	v_exp_f32_e32 v10, v10
	v_add_f32_e32 v12, 1.0, v12
	v_add_f32_e32 v13, 1.0, v13
	v_add_f32_e32 v14, 1.0, v14
	v_add_f32_e32 v15, 1.0, v15
	v_rcp_f32_e32 v14, v14
	v_rcp_f32_e32 v15, v15
	v_mul_f32_e32 v4, 0xbfb8aa3b, v4
	s_waitcnt vmcnt(5)
; __device__ __forceinline__ void load8(const bf16_t* src, float* v) { const u32x4 w = *(const u32x4*)src; v[0] = bf_lo(w.x); v[1] = bf_hi(w.x); v[2] = bf_lo(w.y); v[3] = bf_hi(w.y); v[4] = bf_lo(w.z); v[5] = bf_hi(w.z); v[6] = bf_lo(w.w); v[7] = bf_hi(w.w); }
; __device__ __forceinline__ float sigmoidf_(float v) { return __builtin_amdgcn_rcpf(1.f + __builtin_amdgcn_exp2f(-v * LOG2E)); }
;     __device__ __forceinline__ void operator()(const pg8::f32x4 (&acc)[2][2][4][2], const pg8::Unit& u, int wr, int wc, int fr, int fq) const {
;     ...
;                 if constexpr (KIND == EK_FIN) rs = __builtin_amdgcn_rsqf(a.ssq0[row] * (1.f / 2048.f) + EPS);
;     ...
;                     } else if constexpr (KIND == EK_FIN) {
;                         const int c = pn * 256 + cl; const size_t off = (size_t)row * 2048 + c; float e[8]; load8(a.g0 + off, e);
;                         const f32x4 x0 = *(const f32x4*)(a.outf + off), x1 = *(const f32x4*)(a.outf + off + 4);
;                         const f32x4 g0 = *(const f32x4*)(a.gv + c), g1 = *(const f32x4*)(a.gv + c + 4);
;                         f32x4 r0, r1;
; #pragma unroll
;                         for (int j = 0; j < 4; ++j) { r0[j] = x0[j] + sigmoidf_(v[j]) * (e[j] * rs * g0[j]); r1[j] = x1[j] + sigmoidf_(v[4 + j]) * (e[4 + j] * rs * g1[j]); }
;                         *(f32x4*)(a.outf + off) = r0; *(f32x4*)(a.outf + off + 4) = r1;
;                     }
	v_fmamk_f32 v126, v124, 0x3a000000, v158
	v_rsq_f32_e32 v126, v126
	s_waitcnt vmcnt(4)
	v_lshlrev_b32_e32 v92, 16, v98
	v_and_b32_e32 v93, 0xffff0000, v98
	v_lshlrev_b32_e32 v124, 16, v100
	v_and_b32_e32 v125, 0xffff0000, v100
	v_lshlrev_b32_e32 v98, 16, v99
	v_and_b32_e32 v99, 0xffff0000, v99
	v_lshlrev_b32_e32 v100, 16, v101
	v_and_b32_e32 v101, 0xffff0000, v101
	v_pk_mul_f32 v[92:93], v[126:127], v[92:93] op_sel_hi:[0,1]
	v_pk_mul_f32 v[124:125], v[126:127], v[124:125] op_sel_hi:[0,1]
	v_pk_mul_f32 v[98:99], v[126:127], v[98:99] op_sel_hi:[0,1]
	v_pk_mul_f32 v[100:101], v[126:127], v[100:101] op_sel_hi:[0,1]
	s_waitcnt vmcnt(3)
	v_pk_mul_f32 v[92:93], v[92:93], v[102:103]
	s_waitcnt vmcnt(2)
	v_pk_mul_f32 v[102:103], v[124:125], v[106:107]
	v_pk_mul_f32 v[98:99], v[98:99], v[104:105]
	v_pk_mul_f32 v[100:101], v[100:101], v[108:109]
	s_waitcnt vmcnt(1)
	v_pk_fma_f32 v[88:89], v[88:89], v[92:93], v[110:111]
	s_waitcnt vmcnt(0)
	v_pk_fma_f32 v[92:93], v[90:91], v[102:103], v[114:115]
	v_pk_fma_f32 v[90:91], v[94:95], v[98:99], v[112:113]
	v_pk_fma_f32 v[94:95], v[122:123], v[100:101], v[116:117]
	global_store_dwordx4 v[96:97], v[88:91], off nt
	global_store_dwordx4 v[96:97], v[92:95], off offset:16 nt
	global_load_dwordx4 v[88:91], v[118:119], off
	s_nop 0
	global_load_dwordx4 v[92:95], v[144:145], off offset:512
	global_load_dwordx4 v[98:101], v[144:145], off offset:528
	global_load_dwordx4 v[102:105], v[96:97], off offset:512
	global_load_dwordx4 v[106:109], v[96:97], off offset:528
	v_exp_f32_e32 v116, v80
	v_exp_f32_e32 v117, v81
	v_or_b32_e32 v80, 48, v148
	v_ashrrev_i32_e32 v81, 31, v80
	v_lshl_add_u64 v[110:111], v[80:81], 2, s[12:13]
	v_lshlrev_b64 v[112:113], 11, v[80:81]
	v_add_f32_e32 v80, 1.0, v84
	v_add_f32_e32 v81, 1.0, v116
	v_add_f32_e32 v84, 1.0, v85
	v_add_f32_e32 v85, 1.0, v117
	v_add_f32_e32 v118, 1.0, v82
	v_add_f32_e32 v119, 1.0, v83
	v_rcp_f32_e32 v80, v80
	v_rcp_f32_e32 v82, v81
	v_rcp_f32_e32 v81, v84
	v_rcp_f32_e32 v83, v85
	v_rcp_f32_e32 v118, v118
	v_rcp_f32_e32 v119, v119
	v_lshl_add_u64 v[114:115], v[112:113], 0, v[146:147]
	v_lshl_add_u64 v[116:117], v[114:115], 1, s[10:11]
	v_mul_f32_e32 v0, 0xbfb8aa3b, v0
	v_mul_f32_e32 v5, 0xbfb8aa3b, v5
	v_mul_f32_e32 v1, 0xbfb8aa3b, v1
	v_mul_f32_e32 v6, 0xbfb8aa3b, v6
	v_mul_f32_e32 v7, 0xbfb8aa3b, v7
	v_mul_f32_e32 v2, 0xbfb8aa3b, v2
	v_mul_f32_e32 v3, 0xbfb8aa3b, v3
	v_exp_f32_e32 v4, v4
	v_exp_f32_e32 v0, v0
	v_exp_f32_e32 v5, v5
	v_exp_f32_e32 v1, v1
	v_exp_f32_e32 v6, v6
	v_exp_f32_e32 v7, v7
	v_exp_f32_e32 v2, v2
	v_exp_f32_e32 v3, v3
	v_add_f32_e32 v4, 1.0, v4
	v_add_f32_e32 v5, 1.0, v5
	v_add_f32_e32 v6, 1.0, v6
	v_add_f32_e32 v7, 1.0, v7
	v_rcp_f32_e32 v6, v6
	v_rcp_f32_e32 v7, v7
	s_andn2_b64 vcc, exec, s[0:1]
	s_mov_b64 s[0:1], -1
	s_waitcnt vmcnt(4)
	v_lshlrev_b32_e32 v84, 16, v88
	v_and_b32_e32 v85, 0xffff0000, v88
	v_lshlrev_b32_e32 v122, 16, v90
	v_and_b32_e32 v123, 0xffff0000, v90
	v_lshlrev_b32_e32 v88, 16, v89
	v_and_b32_e32 v89, 0xffff0000, v89
	v_lshlrev_b32_e32 v90, 16, v91
	v_and_b32_e32 v91, 0xffff0000, v91
	v_pk_mul_f32 v[84:85], v[126:127], v[84:85] op_sel_hi:[0,1]
	v_pk_mul_f32 v[122:123], v[126:127], v[122:123] op_sel_hi:[0,1]
	v_pk_mul_f32 v[88:89], v[126:127], v[88:89] op_sel_hi:[0,1]
	v_pk_mul_f32 v[90:91], v[126:127], v[90:91] op_sel_hi:[0,1]
	s_waitcnt vmcnt(3)
	v_pk_mul_f32 v[84:85], v[84:85], v[92:93]
	s_waitcnt vmcnt(2)
	v_pk_mul_f32 v[92:93], v[122:123], v[98:99]
	v_pk_mul_f32 v[88:89], v[88:89], v[94:95]
	v_pk_mul_f32 v[90:91], v[90:91], v[100:101]
	s_waitcnt vmcnt(1)
	v_pk_fma_f32 v[80:81], v[80:81], v[84:85], v[102:103]
	s_waitcnt vmcnt(0)
	v_pk_fma_f32 v[84:85], v[82:83], v[92:93], v[106:107]
	v_pk_fma_f32 v[82:83], v[86:87], v[88:89], v[104:105]
	v_pk_fma_f32 v[86:87], v[118:119], v[90:91], v[108:109]
	global_store_dwordx4 v[96:97], v[80:83], off offset:512 nt
	global_store_dwordx4 v[96:97], v[84:87], off offset:528 nt
	global_load_dword v106, v[110:111], off
	s_nop 0
	global_load_dwordx4 v[82:85], v[116:117], off
	global_load_dwordx4 v[86:89], v[144:145], off
	global_load_dwordx4 v[90:93], v[144:145], off offset:16
	v_lshl_add_u64 v[80:81], v[114:115], 2, s[4:5]
	global_load_dwordx4 v[94:97], v[80:81], off
	global_load_dwordx4 v[98:101], v[80:81], off offset:16
	v_exp_f32_e32 v103, v73
	v_exp_f32_e32 v102, v72
	v_add_f32_e32 v108, 1.0, v75
	v_lshl_add_u64 v[72:73], v[112:113], 0, v[120:121]
	v_add_f32_e32 v105, 1.0, v103
	v_rcp_f32_e32 v75, v105
	v_rcp_f32_e32 v105, v108
	v_add_f32_e32 v104, 1.0, v102
	v_add_f32_e32 v107, 1.0, v74
	v_lshl_add_u64 v[102:103], v[72:73], 1, s[10:11]
	v_rcp_f32_e32 v72, v76
	v_rcp_f32_e32 v74, v104
	v_rcp_f32_e32 v73, v77
	v_rcp_f32_e32 v104, v107
	s_waitcnt vmcnt(5)
	v_fmamk_f32 v108, v106, 0x3a000000, v158
	v_rsq_f32_e32 v108, v108
	s_waitcnt vmcnt(4)
	v_lshlrev_b32_e32 v76, 16, v82
	v_and_b32_e32 v77, 0xffff0000, v82
	v_lshlrev_b32_e32 v106, 16, v84
	v_and_b32_e32 v107, 0xffff0000, v84
	v_lshlrev_b32_e32 v82, 16, v83
	v_and_b32_e32 v83, 0xffff0000, v83
	v_lshlrev_b32_e32 v84, 16, v85
	v_and_b32_e32 v85, 0xffff0000, v85
	v_pk_mul_f32 v[76:77], v[108:109], v[76:77] op_sel_hi:[0,1]
	v_pk_mul_f32 v[106:107], v[108:109], v[106:107] op_sel_hi:[0,1]
	v_pk_mul_f32 v[82:83], v[108:109], v[82:83] op_sel_hi:[0,1]
	v_pk_mul_f32 v[84:85], v[108:109], v[84:85] op_sel_hi:[0,1]
	s_waitcnt vmcnt(3)
	v_pk_mul_f32 v[76:77], v[76:77], v[86:87]
	s_waitcnt vmcnt(2)
	v_pk_mul_f32 v[86:87], v[106:107], v[90:91]
	v_pk_mul_f32 v[82:83], v[82:83], v[88:89]
	v_pk_mul_f32 v[84:85], v[84:85], v[92:93]
	s_waitcnt vmcnt(1)
	v_pk_fma_f32 v[72:73], v[72:73], v[76:77], v[94:95]
	s_waitcnt vmcnt(0)
; __device__ __forceinline__ void load8(const bf16_t* src, float* v) { const u32x4 w = *(const u32x4*)src; v[0] = bf_lo(w.x); v[1] = bf_hi(w.x); v[2] = bf_lo(w.y); v[3] = bf_hi(w.y); v[4] = bf_lo(w.z); v[5] = bf_hi(w.z); v[6] = bf_lo(w.w); v[7] = bf_hi(w.w); }
; __device__ __forceinline__ float sigmoidf_(float v) { return __builtin_amdgcn_rcpf(1.f + __builtin_amdgcn_exp2f(-v * LOG2E)); }
;     __device__ __forceinline__ void operator()(const pg8::f32x4 (&acc)[2][2][4][2], const pg8::Unit& u, int wr, int wc, int fr, int fq) const {
;     ...
;                     } else if constexpr (KIND == EK_FIN) {
;                         const int c = pn * 256 + cl; const size_t off = (size_t)row * 2048 + c; float e[8]; load8(a.g0 + off, e);
;                         const f32x4 x0 = *(const f32x4*)(a.outf + off), x1 = *(const f32x4*)(a.outf + off + 4);
;                         const f32x4 g0 = *(const f32x4*)(a.gv + c), g1 = *(const f32x4*)(a.gv + c + 4);
;                         f32x4 r0, r1;
; #pragma unroll
;                         for (int j = 0; j < 4; ++j) { r0[j] = x0[j] + sigmoidf_(v[j]) * (e[j] * rs * g0[j]); r1[j] = x1[j] + sigmoidf_(v[4 + j]) * (e[4 + j] * rs * g1[j]); }
;                         *(f32x4*)(a.outf + off) = r0; *(f32x4*)(a.outf + off + 4) = r1;
;                     }
	v_pk_fma_f32 v[76:77], v[74:75], v[86:87], v[98:99]
	v_pk_fma_f32 v[74:75], v[78:79], v[82:83], v[96:97]
	v_pk_fma_f32 v[78:79], v[104:105], v[84:85], v[100:101]
	global_store_dwordx4 v[80:81], v[72:75], off nt
	global_store_dwordx4 v[80:81], v[76:79], off offset:16 nt
	global_load_dwordx4 v[72:75], v[102:103], off
	s_nop 0
	global_load_dwordx4 v[76:79], v[144:145], off offset:512
	global_load_dwordx4 v[82:85], v[144:145], off offset:528
	global_load_dwordx4 v[86:89], v[80:81], off offset:512
	global_load_dwordx4 v[90:93], v[80:81], off offset:528
	v_exp_f32_e32 v100, v64
	v_exp_f32_e32 v101, v65
	v_add_u32_e32 v64, 0x80, v148
	v_ashrrev_i32_e32 v65, 31, v64
	v_lshl_add_u64 v[94:95], v[64:65], 2, s[12:13]
	v_lshlrev_b64 v[96:97], 11, v[64:65]
	v_add_f32_e32 v64, 1.0, v68
	v_add_f32_e32 v65, 1.0, v100
	v_add_f32_e32 v68, 1.0, v69
	v_add_f32_e32 v69, 1.0, v101
	v_add_f32_e32 v102, 1.0, v66
	v_add_f32_e32 v103, 1.0, v67
	v_rcp_f32_e32 v64, v64
	v_rcp_f32_e32 v66, v65
	v_rcp_f32_e32 v65, v68
	v_rcp_f32_e32 v67, v69
	v_rcp_f32_e32 v102, v102
	v_rcp_f32_e32 v103, v103
	v_lshl_add_u64 v[98:99], v[96:97], 0, v[146:147]
	v_lshl_add_u64 v[100:101], v[98:99], 1, s[10:11]
	s_waitcnt vmcnt(4)
	v_lshlrev_b32_e32 v68, 16, v72
	v_and_b32_e32 v69, 0xffff0000, v72
	v_lshlrev_b32_e32 v104, 16, v74
	v_and_b32_e32 v105, 0xffff0000, v74
	v_lshlrev_b32_e32 v72, 16, v73
	v_and_b32_e32 v73, 0xffff0000, v73
	v_lshlrev_b32_e32 v74, 16, v75
	v_and_b32_e32 v75, 0xffff0000, v75
	v_pk_mul_f32 v[68:69], v[108:109], v[68:69] op_sel_hi:[0,1]
	v_pk_mul_f32 v[104:105], v[108:109], v[104:105] op_sel_hi:[0,1]
	v_pk_mul_f32 v[72:73], v[108:109], v[72:73] op_sel_hi:[0,1]
	v_pk_mul_f32 v[74:75], v[108:109], v[74:75] op_sel_hi:[0,1]
	s_waitcnt vmcnt(3)
	v_pk_mul_f32 v[68:69], v[68:69], v[76:77]
	s_waitcnt vmcnt(2)
	v_pk_mul_f32 v[76:77], v[104:105], v[82:83]
	v_pk_mul_f32 v[72:73], v[72:73], v[78:79]
	v_pk_mul_f32 v[74:75], v[74:75], v[84:85]
	s_waitcnt vmcnt(1)
	v_pk_fma_f32 v[64:65], v[64:65], v[68:69], v[86:87]
	s_waitcnt vmcnt(0)
	v_pk_fma_f32 v[68:69], v[66:67], v[76:77], v[90:91]
	v_pk_fma_f32 v[66:67], v[70:71], v[72:73], v[88:89]
	v_pk_fma_f32 v[70:71], v[102:103], v[74:75], v[92:93]
	global_store_dwordx4 v[80:81], v[64:67], off offset:512 nt
	global_store_dwordx4 v[80:81], v[68:71], off offset:528 nt
	global_load_dword v90, v[94:95], off
	s_nop 0
	global_load_dwordx4 v[66:69], v[100:101], off
	global_load_dwordx4 v[70:73], v[144:145], off
	global_load_dwordx4 v[74:77], v[144:145], off offset:16
	v_lshl_add_u64 v[64:65], v[98:99], 2, s[4:5]
	global_load_dwordx4 v[78:81], v[64:65], off
	global_load_dwordx4 v[82:85], v[64:65], off offset:16
	v_exp_f32_e32 v87, v57
	v_exp_f32_e32 v86, v56
	v_add_f32_e32 v92, 1.0, v59
	v_lshl_add_u64 v[56:57], v[96:97], 0, v[120:121]
	v_add_f32_e32 v89, 1.0, v87
	v_rcp_f32_e32 v59, v89
	v_rcp_f32_e32 v89, v92
	v_add_f32_e32 v88, 1.0, v86
	v_add_f32_e32 v91, 1.0, v58
	v_lshl_add_u64 v[86:87], v[56:57], 1, s[10:11]
	v_rcp_f32_e32 v56, v60
	v_rcp_f32_e32 v58, v88
	v_rcp_f32_e32 v57, v61
	v_rcp_f32_e32 v88, v91
	s_waitcnt vmcnt(5)
	v_fmamk_f32 v92, v90, 0x3a000000, v158
	v_rsq_f32_e32 v92, v92
	s_waitcnt vmcnt(4)
	v_lshlrev_b32_e32 v60, 16, v66
	v_and_b32_e32 v61, 0xffff0000, v66
	v_lshlrev_b32_e32 v90, 16, v68
	v_and_b32_e32 v91, 0xffff0000, v68
	v_lshlrev_b32_e32 v66, 16, v67
	v_and_b32_e32 v67, 0xffff0000, v67
	v_lshlrev_b32_e32 v68, 16, v69
	v_and_b32_e32 v69, 0xffff0000, v69
	v_pk_mul_f32 v[60:61], v[92:93], v[60:61] op_sel_hi:[0,1]
	v_pk_mul_f32 v[90:91], v[92:93], v[90:91] op_sel_hi:[0,1]
	v_pk_mul_f32 v[66:67], v[92:93], v[66:67] op_sel_hi:[0,1]
	v_pk_mul_f32 v[68:69], v[92:93], v[68:69] op_sel_hi:[0,1]
	s_waitcnt vmcnt(3)
	v_pk_mul_f32 v[60:61], v[60:61], v[70:71]
	s_waitcnt vmcnt(2)
	v_pk_mul_f32 v[70:71], v[90:91], v[74:75]
	v_pk_mul_f32 v[66:67], v[66:67], v[72:73]
	v_pk_mul_f32 v[68:69], v[68:69], v[76:77]
	s_waitcnt vmcnt(1)
	v_pk_fma_f32 v[56:57], v[56:57], v[60:61], v[78:79]
	s_waitcnt vmcnt(0)
	v_pk_fma_f32 v[60:61], v[58:59], v[70:71], v[82:83]
	v_pk_fma_f32 v[58:59], v[62:63], v[66:67], v[80:81]
	v_pk_fma_f32 v[62:63], v[88:89], v[68:69], v[84:85]
	global_store_dwordx4 v[64:65], v[56:59], off nt
	global_store_dwordx4 v[64:65], v[60:63], off offset:16 nt
	global_load_dwordx4 v[56:59], v[86:87], off
	s_nop 0
	global_load_dwordx4 v[60:63], v[144:145], off offset:512
	global_load_dwordx4 v[66:69], v[144:145], off offset:528
	global_load_dwordx4 v[70:73], v[64:65], off offset:512
	global_load_dwordx4 v[74:77], v[64:65], off offset:528
	v_exp_f32_e32 v84, v48
	v_exp_f32_e32 v85, v49
	v_add_u32_e32 v48, 0x90, v148
	v_ashrrev_i32_e32 v49, 31, v48
	v_lshl_add_u64 v[78:79], v[48:49], 2, s[12:13]
	v_lshlrev_b64 v[80:81], 11, v[48:49]
	v_add_f32_e32 v48, 1.0, v52
	v_add_f32_e32 v49, 1.0, v84
	v_add_f32_e32 v52, 1.0, v53
	v_add_f32_e32 v53, 1.0, v85
	v_add_f32_e32 v86, 1.0, v50
	v_add_f32_e32 v87, 1.0, v51
	v_rcp_f32_e32 v48, v48
	v_rcp_f32_e32 v50, v49
	v_rcp_f32_e32 v49, v52
	v_rcp_f32_e32 v51, v53
	v_rcp_f32_e32 v86, v86
	v_rcp_f32_e32 v87, v87
	v_lshl_add_u64 v[82:83], v[80:81], 0, v[146:147]
	v_lshl_add_u64 v[84:85], v[82:83], 1, s[10:11]
	s_waitcnt vmcnt(4)
	v_lshlrev_b32_e32 v52, 16, v56
	v_and_b32_e32 v53, 0xffff0000, v56
	v_lshlrev_b32_e32 v88, 16, v58
	v_and_b32_e32 v89, 0xffff0000, v58
	v_lshlrev_b32_e32 v56, 16, v57
	v_and_b32_e32 v57, 0xffff0000, v57
	v_lshlrev_b32_e32 v58, 16, v59
	v_and_b32_e32 v59, 0xffff0000, v59
	v_pk_mul_f32 v[52:53], v[92:93], v[52:53] op_sel_hi:[0,1]
	v_pk_mul_f32 v[88:89], v[92:93], v[88:89] op_sel_hi:[0,1]
	v_pk_mul_f32 v[56:57], v[92:93], v[56:57] op_sel_hi:[0,1]
	v_pk_mul_f32 v[58:59], v[92:93], v[58:59] op_sel_hi:[0,1]
	s_waitcnt vmcnt(3)
; __device__ __forceinline__ void load8(const bf16_t* src, float* v) { const u32x4 w = *(const u32x4*)src; v[0] = bf_lo(w.x); v[1] = bf_hi(w.x); v[2] = bf_lo(w.y); v[3] = bf_hi(w.y); v[4] = bf_lo(w.z); v[5] = bf_hi(w.z); v[6] = bf_lo(w.w); v[7] = bf_hi(w.w); }
; __device__ __forceinline__ float sigmoidf_(float v) { return __builtin_amdgcn_rcpf(1.f + __builtin_amdgcn_exp2f(-v * LOG2E)); }
;     __device__ __forceinline__ void operator()(const pg8::f32x4 (&acc)[2][2][4][2], const pg8::Unit& u, int wr, int wc, int fr, int fq) const {
;     ...
;                 if constexpr (KIND == EK_Q || KIND == EK_KV) rs = __builtin_amdgcn_rsqf(a.ssq0[row] * (1.f / 512.f) + EPS);
;                 if constexpr (KIND == EK_FIN) rs = __builtin_amdgcn_rsqf(a.ssq0[row] * (1.f / 2048.f) + EPS);
;     ...
;                     } else if constexpr (KIND == EK_FIN) {
;                         const int c = pn * 256 + cl; const size_t off = (size_t)row * 2048 + c; float e[8]; load8(a.g0 + off, e);
;                         const f32x4 x0 = *(const f32x4*)(a.outf + off), x1 = *(const f32x4*)(a.outf + off + 4);
;                         const f32x4 g0 = *(const f32x4*)(a.gv + c), g1 = *(const f32x4*)(a.gv + c + 4);
;                         f32x4 r0, r1;
; #pragma unroll
;                         for (int j = 0; j < 4; ++j) { r0[j] = x0[j] + sigmoidf_(v[j]) * (e[j] * rs * g0[j]); r1[j] = x1[j] + sigmoidf_(v[4 + j]) * (e[4 + j] * rs * g1[j]); }
;                         *(f32x4*)(a.outf + off) = r0; *(f32x4*)(a.outf + off + 4) = r1;
	v_pk_mul_f32 v[52:53], v[52:53], v[60:61]
	s_waitcnt vmcnt(2)
	v_pk_mul_f32 v[60:61], v[88:89], v[66:67]
	v_pk_mul_f32 v[56:57], v[56:57], v[62:63]
	v_pk_mul_f32 v[58:59], v[58:59], v[68:69]
	s_waitcnt vmcnt(1)
	v_pk_fma_f32 v[48:49], v[48:49], v[52:53], v[70:71]
	s_waitcnt vmcnt(0)
	v_pk_fma_f32 v[52:53], v[50:51], v[60:61], v[74:75]
	v_pk_fma_f32 v[50:51], v[54:55], v[56:57], v[72:73]
	v_pk_fma_f32 v[54:55], v[86:87], v[58:59], v[76:77]
	global_store_dwordx4 v[64:65], v[48:51], off offset:512 nt
	global_store_dwordx4 v[64:65], v[52:55], off offset:528 nt
	global_load_dword v74, v[78:79], off
	s_nop 0
	global_load_dwordx4 v[50:53], v[84:85], off
	global_load_dwordx4 v[54:57], v[144:145], off
	global_load_dwordx4 v[58:61], v[144:145], off offset:16
	v_lshl_add_u64 v[48:49], v[82:83], 2, s[4:5]
	global_load_dwordx4 v[62:65], v[48:49], off
	global_load_dwordx4 v[66:69], v[48:49], off offset:16
	v_exp_f32_e32 v71, v41
	v_exp_f32_e32 v70, v40
	v_add_f32_e32 v76, 1.0, v43
	v_lshl_add_u64 v[40:41], v[80:81], 0, v[120:121]
	v_add_f32_e32 v73, 1.0, v71
	v_rcp_f32_e32 v43, v73
	v_rcp_f32_e32 v73, v76
	v_add_f32_e32 v72, 1.0, v70
	v_add_f32_e32 v75, 1.0, v42
	v_lshl_add_u64 v[70:71], v[40:41], 1, s[10:11]
	v_rcp_f32_e32 v40, v44
	v_rcp_f32_e32 v42, v72
	v_rcp_f32_e32 v41, v45
	v_rcp_f32_e32 v72, v75
	s_waitcnt vmcnt(5)
	v_fmamk_f32 v76, v74, 0x3a000000, v158
	v_rsq_f32_e32 v76, v76
	s_waitcnt vmcnt(4)
	v_lshlrev_b32_e32 v44, 16, v50
	v_and_b32_e32 v45, 0xffff0000, v50
	v_lshlrev_b32_e32 v74, 16, v52
	v_and_b32_e32 v75, 0xffff0000, v52
	v_lshlrev_b32_e32 v50, 16, v51
	v_and_b32_e32 v51, 0xffff0000, v51
	v_lshlrev_b32_e32 v52, 16, v53
	v_and_b32_e32 v53, 0xffff0000, v53
	v_pk_mul_f32 v[44:45], v[76:77], v[44:45] op_sel_hi:[0,1]
	v_pk_mul_f32 v[74:75], v[76:77], v[74:75] op_sel_hi:[0,1]
	v_pk_mul_f32 v[50:51], v[76:77], v[50:51] op_sel_hi:[0,1]
	v_pk_mul_f32 v[52:53], v[76:77], v[52:53] op_sel_hi:[0,1]
	s_waitcnt vmcnt(3)
	v_pk_mul_f32 v[44:45], v[44:45], v[54:55]
	s_waitcnt vmcnt(2)
	v_pk_mul_f32 v[54:55], v[74:75], v[58:59]
	v_pk_mul_f32 v[50:51], v[50:51], v[56:57]
	v_pk_mul_f32 v[52:53], v[52:53], v[60:61]
	s_waitcnt vmcnt(1)
	v_pk_fma_f32 v[40:41], v[40:41], v[44:45], v[62:63]
	s_waitcnt vmcnt(0)
	v_pk_fma_f32 v[44:45], v[42:43], v[54:55], v[66:67]
	v_pk_fma_f32 v[42:43], v[46:47], v[50:51], v[64:65]
	v_pk_fma_f32 v[46:47], v[72:73], v[52:53], v[68:69]
	global_store_dwordx4 v[48:49], v[40:43], off nt
	global_store_dwordx4 v[48:49], v[44:47], off offset:16 nt
	global_load_dwordx4 v[40:43], v[70:71], off
	s_nop 0
	global_load_dwordx4 v[44:47], v[144:145], off offset:512
	global_load_dwordx4 v[50:53], v[144:145], off offset:528
	global_load_dwordx4 v[54:57], v[48:49], off offset:512
	global_load_dwordx4 v[58:61], v[48:49], off offset:528
	v_exp_f32_e32 v68, v32
	v_exp_f32_e32 v69, v33
	v_add_u32_e32 v32, 0xa0, v148
	v_ashrrev_i32_e32 v33, 31, v32
	v_lshl_add_u64 v[62:63], v[32:33], 2, s[12:13]
	v_lshlrev_b64 v[64:65], 11, v[32:33]
	v_add_f32_e32 v32, 1.0, v36
	v_add_f32_e32 v33, 1.0, v68
	v_add_f32_e32 v36, 1.0, v37
	v_add_f32_e32 v37, 1.0, v69
	v_add_f32_e32 v70, 1.0, v34
	v_add_f32_e32 v71, 1.0, v35
	v_rcp_f32_e32 v32, v32
	v_rcp_f32_e32 v34, v33
	v_rcp_f32_e32 v33, v36
	v_rcp_f32_e32 v35, v37
	v_rcp_f32_e32 v70, v70
	v_rcp_f32_e32 v71, v71
	v_lshl_add_u64 v[66:67], v[64:65], 0, v[146:147]
	v_lshl_add_u64 v[68:69], v[66:67], 1, s[10:11]
	s_waitcnt vmcnt(4)
	v_lshlrev_b32_e32 v36, 16, v40
	v_and_b32_e32 v37, 0xffff0000, v40
	v_lshlrev_b32_e32 v72, 16, v42
	v_and_b32_e32 v73, 0xffff0000, v42
	v_lshlrev_b32_e32 v40, 16, v41
	v_and_b32_e32 v41, 0xffff0000, v41
	v_lshlrev_b32_e32 v42, 16, v43
	v_and_b32_e32 v43, 0xffff0000, v43
	v_pk_mul_f32 v[36:37], v[76:77], v[36:37] op_sel_hi:[0,1]
	v_pk_mul_f32 v[72:73], v[76:77], v[72:73] op_sel_hi:[0,1]
	v_pk_mul_f32 v[40:41], v[76:77], v[40:41] op_sel_hi:[0,1]
	v_pk_mul_f32 v[42:43], v[76:77], v[42:43] op_sel_hi:[0,1]
	s_waitcnt vmcnt(3)
	v_pk_mul_f32 v[36:37], v[36:37], v[44:45]
	s_waitcnt vmcnt(2)
	v_pk_mul_f32 v[44:45], v[72:73], v[50:51]
	v_pk_mul_f32 v[40:41], v[40:41], v[46:47]
	v_pk_mul_f32 v[42:43], v[42:43], v[52:53]
	s_waitcnt vmcnt(1)
	v_pk_fma_f32 v[32:33], v[32:33], v[36:37], v[54:55]
	s_waitcnt vmcnt(0)
	v_pk_fma_f32 v[36:37], v[34:35], v[44:45], v[58:59]
	v_pk_fma_f32 v[34:35], v[38:39], v[40:41], v[56:57]
	v_pk_fma_f32 v[38:39], v[70:71], v[42:43], v[60:61]
	global_store_dwordx4 v[48:49], v[32:35], off offset:512 nt
	global_store_dwordx4 v[48:49], v[36:39], off offset:528 nt
	global_load_dword v58, v[62:63], off
	s_nop 0
	global_load_dwordx4 v[34:37], v[68:69], off
	global_load_dwordx4 v[38:41], v[144:145], off
	global_load_dwordx4 v[42:45], v[144:145], off offset:16
	v_lshl_add_u64 v[32:33], v[66:67], 2, s[4:5]
	global_load_dwordx4 v[46:49], v[32:33], off
	global_load_dwordx4 v[50:53], v[32:33], off offset:16
	v_exp_f32_e32 v55, v25
	v_exp_f32_e32 v54, v24
	v_add_f32_e32 v60, 1.0, v27
	v_lshl_add_u64 v[24:25], v[64:65], 0, v[120:121]
	v_add_f32_e32 v57, 1.0, v55
	v_rcp_f32_e32 v27, v57
	v_rcp_f32_e32 v57, v60
	v_add_f32_e32 v56, 1.0, v54
	v_add_f32_e32 v59, 1.0, v26
	v_lshl_add_u64 v[54:55], v[24:25], 1, s[10:11]
	v_rcp_f32_e32 v24, v28
	v_rcp_f32_e32 v26, v56
	v_rcp_f32_e32 v25, v29
	v_rcp_f32_e32 v56, v59
	s_waitcnt vmcnt(5)
	v_fmamk_f32 v60, v58, 0x3a000000, v158
	v_rsq_f32_e32 v60, v60
	s_waitcnt vmcnt(4)
	v_lshlrev_b32_e32 v28, 16, v34
	v_and_b32_e32 v29, 0xffff0000, v34
	v_lshlrev_b32_e32 v58, 16, v36
	v_and_b32_e32 v59, 0xffff0000, v36
	v_lshlrev_b32_e32 v34, 16, v35
	v_and_b32_e32 v35, 0xffff0000, v35
	v_lshlrev_b32_e32 v36, 16, v37
	v_and_b32_e32 v37, 0xffff0000, v37
	v_pk_mul_f32 v[28:29], v[60:61], v[28:29] op_sel_hi:[0,1]
	v_pk_mul_f32 v[58:59], v[60:61], v[58:59] op_sel_hi:[0,1]
	v_pk_mul_f32 v[34:35], v[60:61], v[34:35] op_sel_hi:[0,1]
	v_pk_mul_f32 v[36:37], v[60:61], v[36:37] op_sel_hi:[0,1]
	s_waitcnt vmcnt(3)
; __device__ __forceinline__ void load8(const bf16_t* src, float* v) { const u32x4 w = *(const u32x4*)src; v[0] = bf_lo(w.x); v[1] = bf_hi(w.x); v[2] = bf_lo(w.y); v[3] = bf_hi(w.y); v[4] = bf_lo(w.z); v[5] = bf_hi(w.z); v[6] = bf_lo(w.w); v[7] = bf_hi(w.w); }
; __device__ __forceinline__ float sigmoidf_(float v) { return __builtin_amdgcn_rcpf(1.f + __builtin_amdgcn_exp2f(-v * LOG2E)); }
;     __device__ __forceinline__ void operator()(const pg8::f32x4 (&acc)[2][2][4][2], const pg8::Unit& u, int wr, int wc, int fr, int fq) const {
;     ...
;                 if constexpr (KIND == EK_Q || KIND == EK_KV) rs = __builtin_amdgcn_rsqf(a.ssq0[row] * (1.f / 512.f) + EPS);
;                 if constexpr (KIND == EK_FIN) rs = __builtin_amdgcn_rsqf(a.ssq0[row] * (1.f / 2048.f) + EPS);
;     ...
;                     } else if constexpr (KIND == EK_FIN) {
;                         const int c = pn * 256 + cl; const size_t off = (size_t)row * 2048 + c; float e[8]; load8(a.g0 + off, e);
;                         const f32x4 x0 = *(const f32x4*)(a.outf + off), x1 = *(const f32x4*)(a.outf + off + 4);
;                         const f32x4 g0 = *(const f32x4*)(a.gv + c), g1 = *(const f32x4*)(a.gv + c + 4);
;                         f32x4 r0, r1;
; #pragma unroll
;                         for (int j = 0; j < 4; ++j) { r0[j] = x0[j] + sigmoidf_(v[j]) * (e[j] * rs * g0[j]); r1[j] = x1[j] + sigmoidf_(v[4 + j]) * (e[4 + j] * rs * g1[j]); }
;                         *(f32x4*)(a.outf + off) = r0; *(f32x4*)(a.outf + off + 4) = r1;
	v_pk_mul_f32 v[28:29], v[28:29], v[38:39]
	s_waitcnt vmcnt(2)
	v_pk_mul_f32 v[38:39], v[58:59], v[42:43]
	v_pk_mul_f32 v[34:35], v[34:35], v[40:41]
	v_pk_mul_f32 v[36:37], v[36:37], v[44:45]
	s_waitcnt vmcnt(1)
	v_pk_fma_f32 v[24:25], v[24:25], v[28:29], v[46:47]
	s_waitcnt vmcnt(0)
	v_pk_fma_f32 v[28:29], v[26:27], v[38:39], v[50:51]
	v_pk_fma_f32 v[26:27], v[30:31], v[34:35], v[48:49]
	v_pk_fma_f32 v[30:31], v[56:57], v[36:37], v[52:53]
	global_store_dwordx4 v[32:33], v[24:27], off nt
	global_store_dwordx4 v[32:33], v[28:31], off offset:16 nt
	global_load_dwordx4 v[24:27], v[54:55], off
	s_nop 0
	global_load_dwordx4 v[28:31], v[144:145], off offset:512
	global_load_dwordx4 v[34:37], v[144:145], off offset:528
	global_load_dwordx4 v[38:41], v[32:33], off offset:512
	global_load_dwordx4 v[42:45], v[32:33], off offset:528
	v_exp_f32_e32 v52, v16
	v_exp_f32_e32 v53, v17
	v_add_u32_e32 v16, 0xb0, v148
	v_ashrrev_i32_e32 v17, 31, v16
	v_lshl_add_u64 v[46:47], v[16:17], 2, s[12:13]
	v_lshlrev_b64 v[48:49], 11, v[16:17]
	v_add_f32_e32 v16, 1.0, v20
	v_add_f32_e32 v17, 1.0, v52
	v_add_f32_e32 v20, 1.0, v21
	v_add_f32_e32 v21, 1.0, v53
	v_add_f32_e32 v54, 1.0, v18
	v_add_f32_e32 v55, 1.0, v19
	v_rcp_f32_e32 v16, v16
	v_rcp_f32_e32 v18, v17
	v_rcp_f32_e32 v17, v20
	v_rcp_f32_e32 v19, v21
	v_rcp_f32_e32 v54, v54
	v_rcp_f32_e32 v55, v55
	v_lshl_add_u64 v[50:51], v[48:49], 0, v[146:147]
	v_lshl_add_u64 v[52:53], v[50:51], 1, s[10:11]
	s_waitcnt vmcnt(4)
	v_lshlrev_b32_e32 v20, 16, v24
	v_and_b32_e32 v21, 0xffff0000, v24
	v_lshlrev_b32_e32 v56, 16, v26
	v_and_b32_e32 v57, 0xffff0000, v26
	v_lshlrev_b32_e32 v24, 16, v25
	v_and_b32_e32 v25, 0xffff0000, v25
	v_lshlrev_b32_e32 v26, 16, v27
	v_and_b32_e32 v27, 0xffff0000, v27
	v_pk_mul_f32 v[20:21], v[60:61], v[20:21] op_sel_hi:[0,1]
	v_pk_mul_f32 v[56:57], v[60:61], v[56:57] op_sel_hi:[0,1]
	v_pk_mul_f32 v[24:25], v[60:61], v[24:25] op_sel_hi:[0,1]
	v_pk_mul_f32 v[26:27], v[60:61], v[26:27] op_sel_hi:[0,1]
	s_waitcnt vmcnt(3)
	v_pk_mul_f32 v[20:21], v[20:21], v[28:29]
	s_waitcnt vmcnt(2)
	v_pk_mul_f32 v[28:29], v[56:57], v[34:35]
	v_pk_mul_f32 v[24:25], v[24:25], v[30:31]
	v_pk_mul_f32 v[26:27], v[26:27], v[36:37]
	s_waitcnt vmcnt(1)
	v_pk_fma_f32 v[16:17], v[16:17], v[20:21], v[38:39]
	s_waitcnt vmcnt(0)
	v_pk_fma_f32 v[20:21], v[18:19], v[28:29], v[42:43]
	v_pk_fma_f32 v[18:19], v[22:23], v[24:25], v[40:41]
	v_pk_fma_f32 v[22:23], v[54:55], v[26:27], v[44:45]
	global_store_dwordx4 v[32:33], v[16:19], off offset:512 nt
	global_store_dwordx4 v[32:33], v[20:23], off offset:528 nt
	global_load_dword v42, v[46:47], off
	s_nop 0
	global_load_dwordx4 v[18:21], v[52:53], off
	global_load_dwordx4 v[22:25], v[144:145], off
	global_load_dwordx4 v[26:29], v[144:145], off offset:16
	v_lshl_add_u64 v[16:17], v[50:51], 2, s[4:5]
	global_load_dwordx4 v[30:33], v[16:17], off
	global_load_dwordx4 v[34:37], v[16:17], off offset:16
	v_exp_f32_e32 v39, v9
	v_exp_f32_e32 v38, v8
	v_add_f32_e32 v44, 1.0, v11
	v_lshl_add_u64 v[8:9], v[48:49], 0, v[120:121]
	v_add_f32_e32 v41, 1.0, v39
	v_rcp_f32_e32 v11, v41
	v_rcp_f32_e32 v41, v44
	v_add_f32_e32 v40, 1.0, v38
	v_add_f32_e32 v43, 1.0, v10
	v_lshl_add_u64 v[38:39], v[8:9], 1, s[10:11]
	v_rcp_f32_e32 v8, v12
	v_rcp_f32_e32 v10, v40
	v_rcp_f32_e32 v9, v13
	v_rcp_f32_e32 v40, v43
	s_waitcnt vmcnt(5)
	v_fmamk_f32 v44, v42, 0x3a000000, v158
	v_rsq_f32_e32 v44, v44
	s_waitcnt vmcnt(4)
	v_lshlrev_b32_e32 v12, 16, v18
	v_and_b32_e32 v13, 0xffff0000, v18
	v_lshlrev_b32_e32 v42, 16, v20
	v_and_b32_e32 v43, 0xffff0000, v20
	v_lshlrev_b32_e32 v18, 16, v19
	v_and_b32_e32 v19, 0xffff0000, v19
	v_lshlrev_b32_e32 v20, 16, v21
	v_and_b32_e32 v21, 0xffff0000, v21
	v_pk_mul_f32 v[12:13], v[44:45], v[12:13] op_sel_hi:[0,1]
	v_pk_mul_f32 v[42:43], v[44:45], v[42:43] op_sel_hi:[0,1]
	v_pk_mul_f32 v[18:19], v[44:45], v[18:19] op_sel_hi:[0,1]
	v_pk_mul_f32 v[20:21], v[44:45], v[20:21] op_sel_hi:[0,1]
	s_waitcnt vmcnt(3)
	v_pk_mul_f32 v[12:13], v[12:13], v[22:23]
	s_waitcnt vmcnt(2)
	v_pk_mul_f32 v[22:23], v[42:43], v[26:27]
	v_pk_mul_f32 v[18:19], v[18:19], v[24:25]
	v_pk_mul_f32 v[20:21], v[20:21], v[28:29]
	s_waitcnt vmcnt(1)
	v_pk_fma_f32 v[8:9], v[8:9], v[12:13], v[30:31]
	s_waitcnt vmcnt(0)
	v_pk_fma_f32 v[12:13], v[10:11], v[22:23], v[34:35]
	v_pk_fma_f32 v[10:11], v[14:15], v[18:19], v[32:33]
	v_pk_fma_f32 v[14:15], v[40:41], v[20:21], v[36:37]
	global_store_dwordx4 v[16:17], v[8:11], off nt
	global_store_dwordx4 v[16:17], v[12:15], off offset:16 nt
	global_load_dwordx4 v[8:11], v[38:39], off
	s_nop 0
	global_load_dwordx4 v[12:15], v[144:145], off offset:512
	global_load_dwordx4 v[18:21], v[144:145], off offset:528
	global_load_dwordx4 v[22:25], v[16:17], off offset:512
	global_load_dwordx4 v[26:29], v[16:17], off offset:528
	v_add_f32_e32 v30, 1.0, v0
	v_add_f32_e32 v31, 1.0, v1
	v_add_f32_e32 v32, 1.0, v2
	v_add_f32_e32 v33, 1.0, v3
	v_rcp_f32_e32 v0, v4
	v_rcp_f32_e32 v2, v30
	v_rcp_f32_e32 v1, v5
	v_rcp_f32_e32 v3, v31
	v_rcp_f32_e32 v30, v32
	v_rcp_f32_e32 v31, v33
	s_waitcnt vmcnt(4)
	v_lshlrev_b32_e32 v4, 16, v8
	v_and_b32_e32 v5, 0xffff0000, v8
	v_lshlrev_b32_e32 v32, 16, v10
	v_and_b32_e32 v33, 0xffff0000, v10
	v_lshlrev_b32_e32 v8, 16, v9
	v_and_b32_e32 v9, 0xffff0000, v9
	v_lshlrev_b32_e32 v10, 16, v11
	v_and_b32_e32 v11, 0xffff0000, v11
	v_pk_mul_f32 v[4:5], v[44:45], v[4:5] op_sel_hi:[0,1]
	v_pk_mul_f32 v[32:33], v[44:45], v[32:33] op_sel_hi:[0,1]
	v_pk_mul_f32 v[8:9], v[44:45], v[8:9] op_sel_hi:[0,1]
	v_pk_mul_f32 v[10:11], v[44:45], v[10:11] op_sel_hi:[0,1]
	s_waitcnt vmcnt(3)
	v_pk_mul_f32 v[4:5], v[4:5], v[12:13]
	s_waitcnt vmcnt(2)
	v_pk_mul_f32 v[12:13], v[32:33], v[18:19]
	v_pk_mul_f32 v[8:9], v[8:9], v[14:15]
	v_pk_mul_f32 v[10:11], v[10:11], v[20:21]
	s_waitcnt vmcnt(1)
	v_pk_fma_f32 v[0:1], v[0:1], v[4:5], v[22:23]
	s_waitcnt vmcnt(0)
	v_pk_fma_f32 v[4:5], v[2:3], v[12:13], v[26:27]
	v_pk_fma_f32 v[2:3], v[6:7], v[8:9], v[24:25]
	v_pk_fma_f32 v[6:7], v[30:31], v[10:11], v[28:29]
	global_store_dwordx4 v[16:17], v[0:3], off offset:512 nt
	global_store_dwordx4 v[16:17], v[4:7], off offset:528 nt
	s_cbranch_vccnz .LBB0_1554
	s_andn2_b64 vcc, exec, s[8:9]
	s_cbranch_vccnz .LBB0_1553
	s_barrier
	s_branch .LBB0_1553
